# DMA issue moved mid-iteration in attention fast loop + LN1 phase: g/b loads hoisted out of loop and next rows prefetched
# speedup vs baseline: 1.0026x; 1.0026x over previous
; __device__ __forceinline__ int tid_of(int wave_u) { int t; asm volatile("v_mbcnt_lo_u32_b32 %0, -1, 0\n\tv_mbcnt_hi_u32_b32 %0, -1, %0" : "=v"(t)); return t | (wave_u << 6); }
; __device__ __forceinline__ void ln_rows4_b(const bf16* in, float* outf, bf16* outb, const float* g, const float* b, int lane) {
;     u32x4 wa[4], wb[4];
; #pragma unroll
;     for (int r = 0; r < 4; ++r) { wa[r] = __builtin_nontemporal_load((const u32x4*)(in + (size_t)r * D) + lane); wb[r] = __builtin_nontemporal_load((const u32x4*)(in + (size_t)r * D) + 64 + lane); }
; __global__ void __launch_bounds__(NTHREADS) mega(Params p) {
;     ...
; for (int rp_ = 0; rp_ < R_P0; ++rp_) {     if (IN(6)) { const int ln_ = tid_of(wave) & 63; for (int m = gw * 4; m < M; m += NGW * 4) ln_rows4_b(Y1B + (size_t)m * D, nullptr, X1B + (size_t)m * D, p.in[14], p.in[15], ln_); } }
.LBB0_811:
	v_readlane_b32 s4, v251, 0
	v_readlane_b32 s8, v251, 4
	s_cmp_lt_i32 s8, 7
	s_cselect_b64 s[2:3], -1, 0
	v_readlane_b32 s6, v251, 2
	v_readlane_b32 s10, v251, 6
	s_and_b64 s[0:1], s[2:3], s[0:1]
	v_readlane_b32 s4, v251, 39
	s_lshl_b32 s6, s4, 2
	s_andn2_b64 vcc, exec, s[0:1]
	s_lshl_b32 s8, s10, 5
	v_readlane_b32 s5, v251, 1
	v_readlane_b32 s7, v251, 3
	v_readlane_b32 s9, v251, 5
	v_readlane_b32 s11, v251, 7
	s_cbranch_vccnz .LBB0_815
	v_readlane_b32 s0, v251, 39
	s_cmpk_gt_i32 s0, 0x3fff
	v_mbcnt_lo_u32_b32 v0, -1, 0
	v_mbcnt_hi_u32_b32 v0, -1, v0
	s_cbranch_scc1 .LBB0_815
	v_mbcnt_lo_u32_b32 v1, -1, 0
	v_mbcnt_hi_u32_b32 v1, -1, v1
	v_and_b32_e32 v2, 64, v1
	v_add_u32_e32 v2, 64, v2
	v_xor_b32_e32 v3, 1, v1
	v_cmp_lt_i32_e32 vcc, v3, v2
	v_readlane_b32 s12, v251, 54
	v_readlane_b32 s13, v251, 55
	v_cndmask_b32_e32 v3, v1, v3, vcc
	v_lshlrev_b32_e32 v79, 2, v3
	v_xor_b32_e32 v3, 2, v1
	v_cmp_lt_i32_e32 vcc, v3, v2
	v_readlane_b32 s14, v251, 56
	v_readlane_b32 s15, v251, 57
	v_cndmask_b32_e32 v3, v1, v3, vcc
	v_lshlrev_b32_e32 v90, 2, v3
	v_xor_b32_e32 v3, 4, v1
	v_cmp_lt_i32_e32 vcc, v3, v2
	v_readlane_b32 s24, v252, 2
	v_readlane_b32 s25, v252, 3
	v_cndmask_b32_e32 v3, v1, v3, vcc
	v_lshlrev_b32_e32 v91, 2, v3
	v_xor_b32_e32 v3, 8, v1
	v_and_b32_e32 v0, 63, v0
	v_cmp_lt_i32_e32 vcc, v3, v2
	v_readlane_b32 s26, v252, 4
	v_readlane_b32 s27, v252, 5
	s_mov_b64 s[12:13], s[24:25]
	v_cndmask_b32_e32 v3, v1, v3, vcc
	v_lshlrev_b32_e32 v16, 5, v0
	v_mov_b32_e32 v17, 0
	v_readlane_b32 s16, v251, 58
	v_readlane_b32 s17, v251, 59
	v_readlane_b32 s18, v251, 60
	v_readlane_b32 s19, v251, 61
	s_mov_b64 s[14:15], s[26:27]
	v_lshlrev_b32_e32 v92, 2, v3
	v_xor_b32_e32 v3, 16, v1
	v_lshl_add_u64 v[18:19], s[12:13], 0, v[16:17]
	v_lshl_add_u64 v[20:21], s[14:15], 0, v[16:17]
	s_ashr_i32 s7, s6, 31
	v_readlane_b32 s12, v251, 0
	v_cmp_lt_i32_e32 vcc, v3, v2
	s_lshl_b64 s[0:1], s[6:7], 11
	v_readlane_b32 s14, v251, 2
	v_cndmask_b32_e32 v3, v1, v3, vcc
	v_readlane_b32 s15, v251, 3
	s_add_u32 s4, s14, s0
	v_lshlrev_b32_e32 v93, 2, v3
	v_xor_b32_e32 v3, 32, v1
	s_addc_u32 s5, s15, s1
	s_ashr_i32 s9, s8, 31
	v_cmp_lt_i32_e32 vcc, v3, v2
	s_lshl_b64 s[10:11], s[8:9], 11
	v_readlane_b32 s13, v251, 1
	v_cndmask_b32_e32 v1, v1, v3, vcc
	s_add_u32 s12, s12, s0
	v_lshlrev_b32_e32 v94, 2, v1
	v_lshlrev_b32_e32 v16, 4, v0
	s_addc_u32 s13, s13, s1
	v_mov_b32_e32 v95, 0x3727c5ac
	s_mov_b32 s7, 0xf800000
	v_mov_b32_e32 v96, 0x260
	s_mov_b32 s9, s6
	v_readlane_b32 s20, v251, 62
	v_readlane_b32 s21, v251, 63
	v_readlane_b32 s22, v252, 0
	v_readlane_b32 s23, v252, 1
	v_readlane_b32 s16, v251, 4
	v_readlane_b32 s17, v251, 5
	v_readlane_b32 s18, v251, 6
	v_readlane_b32 s19, v251, 7
	global_load_dwordx4 v[200:203], v[18:19], off offset:16
	global_load_dwordx4 v[204:207], v[18:19], off
	global_load_dwordx4 v[208:211], v[20:21], off offset:16
	global_load_dwordx4 v[212:215], v[20:21], off
	global_load_dwordx4 v[216:219], v[18:19], off offset:2064
	global_load_dwordx4 v[220:223], v[18:19], off offset:2048
	global_load_dwordx4 v[224:227], v[20:21], off offset:2064
	global_load_dwordx4 v[228:231], v[20:21], off offset:2048
	s_mov_b64 s[94:95], s[12:13]
	v_lshl_add_u64 v[232:233], s[94:95], 0, v[16:17]
	global_load_dwordx4 v[160:163], v[232:233], off nt
	global_load_dwordx4 v[164:167], v[232:233], off offset:1024 nt
	global_load_dwordx4 v[168:171], v[232:233], off offset:2048 nt
	global_load_dwordx4 v[172:175], v[232:233], off offset:3072 nt
	s_add_u32 s94, s94, 0x1000
	s_addc_u32 s95, s95, 0
	v_lshl_add_u64 v[232:233], s[94:95], 0, v[16:17]
	global_load_dwordx4 v[176:179], v[232:233], off nt
	global_load_dwordx4 v[180:183], v[232:233], off offset:1024 nt
	global_load_dwordx4 v[184:187], v[232:233], off offset:2048 nt
	global_load_dwordx4 v[188:191], v[232:233], off offset:3072 nt
	s_waitcnt vmcnt(0)
.LBB0_814:
	s_nop 0
	s_waitcnt lgkmcnt(0)
	s_add_i32 s9, s9, s8
	s_nop 0
	s_nop 0
	s_waitcnt vmcnt(8)
	v_lshlrev_b32_e32 v24, 16, v160
	v_and_b32_e32 v25, 0xffff0000, v160
	v_add_f32_e32 v4, 0, v24
	v_add_f32_e32 v26, v4, v25
	v_lshlrev_b32_e32 v4, 16, v161
	v_and_b32_e32 v5, 0xffff0000, v161
	v_add_f32_e32 v26, v26, v4
	v_lshlrev_b32_e32 v22, 16, v162
	v_add_f32_e32 v26, v26, v5
	v_and_b32_e32 v23, 0xffff0000, v162
	v_add_f32_e32 v26, v26, v22
	v_lshlrev_b32_e32 v6, 16, v163
	v_add_f32_e32 v26, v26, v23
	v_and_b32_e32 v7, 0xffff0000, v163
	v_add_f32_e32 v26, v26, v6
	v_add_f32_e32 v26, v26, v7
	v_lshlrev_b32_e32 v34, 16, v166
	v_and_b32_e32 v35, 0xffff0000, v166
	v_lshlrev_b32_e32 v10, 16, v164
	v_and_b32_e32 v28, 0xffff0000, v167
	v_lshlrev_b32_e32 v29, 16, v167
	v_and_b32_e32 v11, 0xffff0000, v164
	v_add_f32_e32 v8, v26, v10
	v_add_f32_e32 v26, v8, v11
	v_lshlrev_b32_e32 v8, 16, v165
	v_and_b32_e32 v9, 0xffff0000, v165
	v_add_f32_e32 v26, v26, v8
	v_add_f32_e32 v26, v26, v9
	v_add_f32_e32 v26, v26, v34
	v_add_f32_e32 v26, v26, v35
	v_add_f32_e32 v26, v26, v29
	v_add_f32_e32 v26, v26, v28
	ds_bpermute_b32 v27, v79, v26
	s_waitcnt lgkmcnt(0)
	v_add_f32_e32 v26, v26, v27
	ds_bpermute_b32 v27, v90, v26
	s_waitcnt lgkmcnt(0)
	v_add_f32_e32 v26, v26, v27
	ds_bpermute_b32 v27, v91, v26
	s_waitcnt lgkmcnt(0)
	v_add_f32_e32 v26, v26, v27
	ds_bpermute_b32 v27, v92, v26
	s_waitcnt lgkmcnt(0)
	v_add_f32_e32 v26, v26, v27
	ds_bpermute_b32 v27, v93, v26
	s_waitcnt lgkmcnt(0)
	v_add_f32_e32 v26, v26, v27
	ds_bpermute_b32 v27, v94, v26
	s_waitcnt lgkmcnt(0)
; __device__ __forceinline__ void ln_rows4_b(const bf16* in, float* outf, bf16* outb, const float* g, const float* b, int lane) {
;     ...
;     float v[4][16], s[4], s2[4];
; #pragma unroll
;     for (int r = 0; r < 4; ++r) { s[r] = 0.f;
; #pragma unroll
;         for (int i = 0; i < 4; ++i) { v[r][2 * i] = __uint_as_float(wa[r][i] << 16); v[r][2 * i + 1] = __uint_as_float(wa[r][i] & 0xffff0000u); v[r][8 + 2 * i] = __uint_as_float(wb[r][i] << 16); v[r][8 + 2 * i + 1] = __uint_as_float(wb[r][i] & 0xffff0000u); }
; #pragma unroll
;         for (int i = 0; i < 16; ++i) s[r] += v[r][i]; }
; #pragma unroll
;     for (int o = 1; o < 64; o <<= 1) {
; #pragma unroll
;         for (int r = 0; r < 4; ++r) s[r] += __shfl_xor(s[r], o); }
; #pragma unroll
;     for (int r = 0; r < 4; ++r) { const float mean = s[r] * (1.f / D); s2[r] = 0.f;
; #pragma unroll
;         for (int i = 0; i < 16; ++i) { v[r][i] -= mean; s2[r] += v[r][i] * v[r][i]; } }
	v_add_f32_e32 v26, v26, v27
	v_mul_f32_e32 v36, 0x3a800000, v26
	v_pk_add_f32 v[80:81], v[24:25], v[36:37] op_sel_hi:[1,0] neg_lo:[0,1] neg_hi:[0,1]
	v_pk_add_f32 v[84:85], v[4:5], v[36:37] op_sel_hi:[1,0] neg_lo:[0,1] neg_hi:[0,1]
	v_pk_mul_f32 v[50:51], v[80:81], v[80:81]
	v_pk_mul_f32 v[4:5], v[84:85], v[84:85]
	v_add_f32_e32 v50, v50, v51
	v_pk_add_f32 v[82:83], v[22:23], v[36:37] op_sel_hi:[1,0] neg_lo:[0,1] neg_hi:[0,1]
	v_add_f32_e32 v4, v4, v50
	v_pk_mul_f32 v[52:53], v[82:83], v[82:83]
	v_add_f32_e32 v4, v5, v4
	v_pk_add_f32 v[86:87], v[6:7], v[36:37] op_sel_hi:[1,0] neg_lo:[0,1] neg_hi:[0,1]
	v_add_f32_e32 v4, v52, v4
	v_pk_mul_f32 v[6:7], v[86:87], v[86:87]
	v_add_f32_e32 v4, v53, v4
	v_pk_add_f32 v[22:23], v[10:11], v[36:37] op_sel_hi:[1,0] neg_lo:[0,1] neg_hi:[0,1]
	v_add_f32_e32 v4, v6, v4
	v_pk_mul_f32 v[10:11], v[22:23], v[22:23]
	v_add_f32_e32 v4, v7, v4
	v_pk_add_f32 v[26:27], v[8:9], v[36:37] op_sel_hi:[1,0] neg_lo:[0,1] neg_hi:[0,1]
	v_add_f32_e32 v4, v10, v4
	v_pk_mul_f32 v[8:9], v[26:27], v[26:27]
	v_add_f32_e32 v4, v11, v4
	v_pk_add_f32 v[24:25], v[34:35], v[36:37] op_sel_hi:[1,0] neg_lo:[0,1] neg_hi:[0,1]
	v_add_f32_e32 v4, v8, v4
	v_pk_mul_f32 v[34:35], v[24:25], v[24:25]
	v_add_f32_e32 v4, v9, v4
	v_lshlrev_b32_e32 v8, 16, v168
	v_pk_add_f32 v[28:29], v[28:29], v[36:37] op_sel_hi:[1,0] neg_lo:[0,1] neg_hi:[0,1]
	v_add_f32_e32 v4, v34, v4
	v_and_b32_e32 v9, 0xffff0000, v168
	v_add_f32_e32 v10, 0, v8
	v_pk_mul_f32 v[36:37], v[28:29], v[28:29]
	v_add_f32_e32 v4, v35, v4
	v_add_f32_e32 v12, v10, v9
	v_lshlrev_b32_e32 v10, 16, v169
	v_add_f32_e32 v4, v37, v4
	v_and_b32_e32 v11, 0xffff0000, v169
	v_add_f32_e32 v12, v12, v10
	v_add_f32_e32 v78, v36, v4
	v_lshlrev_b32_e32 v4, 16, v170
	v_add_f32_e32 v12, v12, v11
	v_and_b32_e32 v5, 0xffff0000, v170
	v_add_f32_e32 v12, v12, v4
	v_lshlrev_b32_e32 v6, 16, v171
	v_add_f32_e32 v12, v12, v5
	v_and_b32_e32 v7, 0xffff0000, v171
	v_add_f32_e32 v12, v12, v6
	v_add_f32_e32 v34, v12, v7
	v_lshlrev_b32_e32 v14, 16, v174
	v_and_b32_e32 v15, 0xffff0000, v174
	v_lshlrev_b32_e32 v32, 16, v172
	v_and_b32_e32 v12, 0xffff0000, v175
	v_lshlrev_b32_e32 v13, 16, v175
	v_and_b32_e32 v33, 0xffff0000, v172
	v_add_f32_e32 v30, v34, v32
	v_add_f32_e32 v30, v30, v33
	v_lshlrev_b32_e32 v34, 16, v173
	v_and_b32_e32 v35, 0xffff0000, v173
	v_add_f32_e32 v30, v30, v34
	v_add_f32_e32 v30, v30, v35
	v_add_f32_e32 v30, v30, v14
	v_add_f32_e32 v30, v30, v15
	v_add_f32_e32 v30, v30, v13
	v_add_f32_e32 v30, v30, v12
	ds_bpermute_b32 v31, v79, v30
	s_waitcnt lgkmcnt(0)
	v_add_f32_e32 v30, v30, v31
	ds_bpermute_b32 v31, v90, v30
	s_waitcnt lgkmcnt(0)
	v_add_f32_e32 v30, v30, v31
	ds_bpermute_b32 v31, v91, v30
	s_waitcnt lgkmcnt(0)
	v_add_f32_e32 v30, v30, v31
	ds_bpermute_b32 v31, v92, v30
	s_waitcnt lgkmcnt(0)
	v_add_f32_e32 v30, v30, v31
	ds_bpermute_b32 v31, v93, v30
	s_waitcnt lgkmcnt(0)
	v_add_f32_e32 v30, v30, v31
	ds_bpermute_b32 v31, v94, v30
	s_waitcnt lgkmcnt(0)
	v_add_f32_e32 v30, v30, v31
	v_mul_f32_e32 v36, 0x3a800000, v30
	v_pk_add_f32 v[70:71], v[8:9], v[36:37] op_sel_hi:[1,0] neg_lo:[0,1] neg_hi:[0,1]
	v_pk_add_f32 v[74:75], v[10:11], v[36:37] op_sel_hi:[1,0] neg_lo:[0,1] neg_hi:[0,1]
	v_pk_mul_f32 v[8:9], v[70:71], v[70:71]
	v_pk_mul_f32 v[10:11], v[74:75], v[74:75]
	v_add_f32_e32 v8, v8, v9
	v_pk_add_f32 v[72:73], v[4:5], v[36:37] op_sel_hi:[1,0] neg_lo:[0,1] neg_hi:[0,1]
	v_add_f32_e32 v8, v10, v8
	v_pk_mul_f32 v[4:5], v[72:73], v[72:73]
	v_add_f32_e32 v8, v11, v8
	v_pk_add_f32 v[76:77], v[6:7], v[36:37] op_sel_hi:[1,0] neg_lo:[0,1] neg_hi:[0,1]
	v_add_f32_e32 v4, v4, v8
	v_pk_mul_f32 v[6:7], v[76:77], v[76:77]
	v_add_f32_e32 v4, v5, v4
	v_pk_add_f32 v[30:31], v[32:33], v[36:37] op_sel_hi:[1,0] neg_lo:[0,1] neg_hi:[0,1]
	v_add_f32_e32 v4, v6, v4
	v_pk_mul_f32 v[50:51], v[30:31], v[30:31]
	v_add_f32_e32 v4, v7, v4
	v_pk_add_f32 v[34:35], v[34:35], v[36:37] op_sel_hi:[1,0] neg_lo:[0,1] neg_hi:[0,1]
	v_add_f32_e32 v4, v50, v4
	v_pk_mul_f32 v[52:53], v[34:35], v[34:35]
	v_add_f32_e32 v4, v51, v4
	v_pk_add_f32 v[32:33], v[14:15], v[36:37] op_sel_hi:[1,0] neg_lo:[0,1] neg_hi:[0,1]
	v_add_f32_e32 v4, v52, v4
	v_pk_mul_f32 v[14:15], v[32:33], v[32:33]
	v_add_f32_e32 v4, v53, v4
	v_pk_add_f32 v[36:37], v[12:13], v[36:37] op_sel_hi:[1,0] neg_lo:[0,1] neg_hi:[0,1]
	v_add_f32_e32 v4, v14, v4
	v_pk_mul_f32 v[12:13], v[36:37], v[36:37]
	v_add_f32_e32 v4, v15, v4
	v_lshlrev_b32_e32 v8, 16, v176
	v_add_f32_e32 v4, v13, v4
	v_and_b32_e32 v9, 0xffff0000, v176
	v_add_f32_e32 v10, 0, v8
	v_add_f32_e32 v88, v12, v4
	v_add_f32_e32 v12, v10, v9
	v_lshlrev_b32_e32 v10, 16, v177
	v_and_b32_e32 v11, 0xffff0000, v177
	v_add_f32_e32 v12, v12, v10
	v_lshlrev_b32_e32 v4, 16, v178
	v_add_f32_e32 v12, v12, v11
	v_and_b32_e32 v5, 0xffff0000, v178
	v_add_f32_e32 v12, v12, v4
	v_lshlrev_b32_e32 v6, 16, v179
	v_add_f32_e32 v12, v12, v5
	v_and_b32_e32 v7, 0xffff0000, v179
	v_add_f32_e32 v12, v12, v6
	v_add_f32_e32 v40, v12, v7
	v_lshlrev_b32_e32 v38, 16, v180
	v_and_b32_e32 v39, 0xffff0000, v180
	v_add_f32_e32 v40, v40, v38
	v_add_f32_e32 v42, v40, v39
	v_lshlrev_b32_e32 v40, 16, v181
	v_and_b32_e32 v41, 0xffff0000, v181
	v_add_f32_e32 v42, v42, v40
	v_lshlrev_b32_e32 v14, 16, v182
	v_add_f32_e32 v42, v42, v41
	v_and_b32_e32 v15, 0xffff0000, v182
	v_add_f32_e32 v42, v42, v14
	v_lshlrev_b32_e32 v13, 16, v183
	v_add_f32_e32 v42, v42, v15
	v_and_b32_e32 v12, 0xffff0000, v183
	v_add_f32_e32 v42, v42, v13
	v_add_f32_e32 v42, v42, v12
	ds_bpermute_b32 v43, v79, v42
	s_waitcnt lgkmcnt(0)
	v_add_f32_e32 v42, v42, v43
	ds_bpermute_b32 v43, v90, v42
	s_waitcnt lgkmcnt(0)
	v_add_f32_e32 v42, v42, v43
	ds_bpermute_b32 v43, v91, v42
	s_waitcnt lgkmcnt(0)
; __device__ __forceinline__ void ln_rows4_b(const bf16* in, float* outf, bf16* outb, const float* g, const float* b, int lane) {
;     ...
;     for (int r = 0; r < 4; ++r) { s[r] = 0.f;
; #pragma unroll
;         for (int i = 0; i < 4; ++i) { v[r][2 * i] = __uint_as_float(wa[r][i] << 16); v[r][2 * i + 1] = __uint_as_float(wa[r][i] & 0xffff0000u); v[r][8 + 2 * i] = __uint_as_float(wb[r][i] << 16); v[r][8 + 2 * i + 1] = __uint_as_float(wb[r][i] & 0xffff0000u); }
; #pragma unroll
;         for (int i = 0; i < 16; ++i) s[r] += v[r][i]; }
; #pragma unroll
;     for (int o = 1; o < 64; o <<= 1) {
; #pragma unroll
;         for (int r = 0; r < 4; ++r) s[r] += __shfl_xor(s[r], o); }
; #pragma unroll
;     for (int r = 0; r < 4; ++r) { const float mean = s[r] * (1.f / D); s2[r] = 0.f;
; #pragma unroll
;         for (int i = 0; i < 16; ++i) { v[r][i] -= mean; s2[r] += v[r][i] * v[r][i]; } }
; #pragma unroll
;     for (int o = 1; o < 64; o <<= 1) {
; #pragma unroll
;         for (int r = 0; r < 4; ++r) s2[r] += __shfl_xor(s2[r], o); }
	v_add_f32_e32 v42, v42, v43
	ds_bpermute_b32 v43, v92, v42
	s_waitcnt lgkmcnt(0)
	v_add_f32_e32 v42, v42, v43
	ds_bpermute_b32 v43, v93, v42
	s_waitcnt lgkmcnt(0)
	v_add_f32_e32 v42, v42, v43
	ds_bpermute_b32 v43, v94, v42
	s_waitcnt lgkmcnt(0)
	v_add_f32_e32 v42, v42, v43
	v_mul_f32_e32 v44, 0x3a800000, v42
	v_pk_add_f32 v[62:63], v[8:9], v[44:45] op_sel_hi:[1,0] neg_lo:[0,1] neg_hi:[0,1]
	v_pk_add_f32 v[66:67], v[10:11], v[44:45] op_sel_hi:[1,0] neg_lo:[0,1] neg_hi:[0,1]
	v_pk_mul_f32 v[8:9], v[62:63], v[62:63]
	v_pk_mul_f32 v[10:11], v[66:67], v[66:67]
	v_add_f32_e32 v8, v8, v9
	v_pk_add_f32 v[64:65], v[4:5], v[44:45] op_sel_hi:[1,0] neg_lo:[0,1] neg_hi:[0,1]
	v_add_f32_e32 v8, v10, v8
	v_pk_mul_f32 v[4:5], v[64:65], v[64:65]
	v_add_f32_e32 v8, v11, v8
	v_pk_add_f32 v[68:69], v[6:7], v[44:45] op_sel_hi:[1,0] neg_lo:[0,1] neg_hi:[0,1]
	v_add_f32_e32 v4, v4, v8
	v_pk_mul_f32 v[6:7], v[68:69], v[68:69]
	v_add_f32_e32 v4, v5, v4
	v_pk_add_f32 v[38:39], v[38:39], v[44:45] op_sel_hi:[1,0] neg_lo:[0,1] neg_hi:[0,1]
	v_add_f32_e32 v4, v6, v4
	v_pk_mul_f32 v[50:51], v[38:39], v[38:39]
	v_add_f32_e32 v4, v7, v4
	v_pk_add_f32 v[42:43], v[40:41], v[44:45] op_sel_hi:[1,0] neg_lo:[0,1] neg_hi:[0,1]
	v_add_f32_e32 v4, v50, v4
	v_pk_mul_f32 v[52:53], v[42:43], v[42:43]
	v_add_f32_e32 v4, v51, v4
	v_pk_add_f32 v[40:41], v[14:15], v[44:45] op_sel_hi:[1,0] neg_lo:[0,1] neg_hi:[0,1]
	v_add_f32_e32 v4, v52, v4
	v_pk_mul_f32 v[14:15], v[40:41], v[40:41]
	v_add_f32_e32 v4, v53, v4
	v_pk_add_f32 v[44:45], v[12:13], v[44:45] op_sel_hi:[1,0] neg_lo:[0,1] neg_hi:[0,1]
	v_add_f32_e32 v4, v14, v4
	v_pk_mul_f32 v[12:13], v[44:45], v[44:45]
	v_add_f32_e32 v4, v15, v4
	v_lshlrev_b32_e32 v8, 16, v184
	v_add_f32_e32 v4, v13, v4
	v_and_b32_e32 v9, 0xffff0000, v184
	v_add_f32_e32 v10, 0, v8
	v_add_f32_e32 v89, v12, v4
	v_add_f32_e32 v12, v10, v9
	v_lshlrev_b32_e32 v10, 16, v185
	v_and_b32_e32 v11, 0xffff0000, v185
	v_add_f32_e32 v12, v12, v10
	v_lshlrev_b32_e32 v4, 16, v186
	v_add_f32_e32 v12, v12, v11
	v_and_b32_e32 v5, 0xffff0000, v186
	v_add_f32_e32 v12, v12, v4
	v_lshlrev_b32_e32 v6, 16, v187
	v_add_f32_e32 v12, v12, v5
	v_and_b32_e32 v7, 0xffff0000, v187
	v_add_f32_e32 v12, v12, v6
	v_add_f32_e32 v46, v12, v7
	v_lshlrev_b32_e32 v14, 16, v190
	v_and_b32_e32 v15, 0xffff0000, v190
	v_lshlrev_b32_e32 v2, 16, v188
	v_and_b32_e32 v12, 0xffff0000, v191
	v_lshlrev_b32_e32 v13, 16, v191
	v_and_b32_e32 v3, 0xffff0000, v188
	v_add_f32_e32 v0, v46, v2
	v_add_f32_e32 v46, v0, v3
	v_lshlrev_b32_e32 v0, 16, v189
	v_and_b32_e32 v1, 0xffff0000, v189
	s_cmp_lt_i32 s9, 0x10000
	s_cbranch_scc0 .Lnopf_p6
	s_add_u32 s94, s12, s10
	s_addc_u32 s95, s13, s11
	v_lshl_add_u64 v[232:233], s[94:95], 0, v[16:17]
	global_load_dwordx4 v[160:163], v[232:233], off nt
	global_load_dwordx4 v[164:167], v[232:233], off offset:1024 nt
	global_load_dwordx4 v[168:171], v[232:233], off offset:2048 nt
	global_load_dwordx4 v[172:175], v[232:233], off offset:3072 nt
	s_add_u32 s94, s94, 0x1000
	s_addc_u32 s95, s95, 0
	v_lshl_add_u64 v[232:233], s[94:95], 0, v[16:17]
	global_load_dwordx4 v[176:179], v[232:233], off nt
	global_load_dwordx4 v[180:183], v[232:233], off offset:1024 nt
	global_load_dwordx4 v[184:187], v[232:233], off offset:2048 nt
	global_load_dwordx4 v[188:191], v[232:233], off offset:3072 nt
.Lnopf_p6:
	v_add_f32_e32 v46, v46, v0
	v_add_f32_e32 v46, v46, v1
	v_add_f32_e32 v46, v46, v14
	v_add_f32_e32 v46, v46, v15
	v_add_f32_e32 v46, v46, v13
	v_add_f32_e32 v46, v46, v12
	ds_bpermute_b32 v47, v79, v46
	s_waitcnt lgkmcnt(0)
	v_add_f32_e32 v46, v46, v47
	ds_bpermute_b32 v47, v90, v46
	s_waitcnt lgkmcnt(0)
	v_add_f32_e32 v46, v46, v47
	ds_bpermute_b32 v47, v91, v46
	s_waitcnt lgkmcnt(0)
	v_add_f32_e32 v46, v46, v47
	ds_bpermute_b32 v47, v92, v46
	s_waitcnt lgkmcnt(0)
	v_add_f32_e32 v46, v46, v47
	ds_bpermute_b32 v47, v93, v46
	s_waitcnt lgkmcnt(0)
	v_add_f32_e32 v46, v46, v47
	ds_bpermute_b32 v47, v94, v46
	s_waitcnt lgkmcnt(0)
	v_add_f32_e32 v46, v46, v47
	v_mul_f32_e32 v52, 0x3a800000, v46
	v_pk_add_f32 v[58:59], v[8:9], v[52:53] op_sel_hi:[1,0] neg_lo:[0,1] neg_hi:[0,1]
	v_pk_add_f32 v[60:61], v[10:11], v[52:53] op_sel_hi:[1,0] neg_lo:[0,1] neg_hi:[0,1]
	v_pk_mul_f32 v[8:9], v[58:59], v[58:59]
	v_pk_mul_f32 v[10:11], v[60:61], v[60:61]
	v_add_f32_e32 v8, v8, v9
	v_pk_add_f32 v[54:55], v[4:5], v[52:53] op_sel_hi:[1,0] neg_lo:[0,1] neg_hi:[0,1]
	v_add_f32_e32 v8, v10, v8
	v_pk_mul_f32 v[4:5], v[54:55], v[54:55]
	v_add_f32_e32 v8, v11, v8
	v_pk_add_f32 v[56:57], v[6:7], v[52:53] op_sel_hi:[1,0] neg_lo:[0,1] neg_hi:[0,1]
	v_add_f32_e32 v4, v4, v8
	v_pk_mul_f32 v[6:7], v[56:57], v[56:57]
	v_add_f32_e32 v4, v5, v4
	v_pk_add_f32 v[46:47], v[2:3], v[52:53] op_sel_hi:[1,0] neg_lo:[0,1] neg_hi:[0,1]
	v_add_f32_e32 v4, v6, v4
	v_pk_mul_f32 v[2:3], v[46:47], v[46:47]
	v_add_f32_e32 v4, v7, v4
	v_pk_add_f32 v[50:51], v[0:1], v[52:53] op_sel_hi:[1,0] neg_lo:[0,1] neg_hi:[0,1]
	v_add_f32_e32 v2, v2, v4
	v_pk_mul_f32 v[0:1], v[50:51], v[50:51]
	v_add_f32_e32 v2, v3, v2
	v_pk_add_f32 v[48:49], v[14:15], v[52:53] op_sel_hi:[1,0] neg_lo:[0,1] neg_hi:[0,1]
	v_add_f32_e32 v0, v0, v2
	v_pk_mul_f32 v[14:15], v[48:49], v[48:49]
	v_add_f32_e32 v0, v1, v0
	v_pk_add_f32 v[52:53], v[12:13], v[52:53] op_sel_hi:[1,0] neg_lo:[0,1] neg_hi:[0,1]
	v_add_f32_e32 v0, v14, v0
	v_pk_mul_f32 v[12:13], v[52:53], v[52:53]
	v_add_f32_e32 v0, v15, v0
	v_add_f32_e32 v0, v13, v0
	v_add_f32_e32 v0, v12, v0
	ds_bpermute_b32 v1, v79, v78
	ds_bpermute_b32 v4, v79, v0
	ds_bpermute_b32 v2, v79, v88
	ds_bpermute_b32 v3, v79, v89
	s_waitcnt lgkmcnt(3)
	v_add_f32_e32 v1, v78, v1
	s_waitcnt lgkmcnt(2)
	v_add_f32_e32 v0, v0, v4
	ds_bpermute_b32 v4, v90, v1
	s_waitcnt lgkmcnt(2)
; __device__ __forceinline__ unsigned cvt_pk_bf16(float lo, float hi) { unsigned r; asm volatile("v_cvt_pk_bf16_f32 %0, %1, %2" : "=v"(r) : "v"(lo), "v"(hi)); return r; }
; __device__ __forceinline__ void ln_rows4_b(const bf16* in, float* outf, bf16* outb, const float* g, const float* b, int lane) {
;     ...
;     for (int o = 1; o < 64; o <<= 1) {
; #pragma unroll
;         for (int r = 0; r < 4; ++r) s2[r] += __shfl_xor(s2[r], o); }
; #pragma unroll
;     for (int h = 0; h < 2; ++h) {
;         const int e0 = h * 512 + 8 * lane;
;         const f32x4 g0 = *(const f32x4*)(g + e0), g1 = *(const f32x4*)(g + e0 + 4), b0 = *(const f32x4*)(b + e0), b1 = *(const f32x4*)(b + e0 + 4);
; #pragma unroll
;         for (int r = 0; r < 4; ++r) {
;             const float rstd = 1.f / sqrtf(s2[r] * (1.f / D) + LN_EPS);
;             const f32x4 o0 = (f32x4){v[r][8 * h + 0], v[r][8 * h + 1], v[r][8 * h + 2], v[r][8 * h + 3]} * rstd * g0 + b0;
;             const f32x4 o1 = (f32x4){v[r][8 * h + 4], v[r][8 * h + 5], v[r][8 * h + 6], v[r][8 * h + 7]} * rstd * g1 + b1;
;             if (outf) { __builtin_nontemporal_store(o0, (f32x4*)(outf + (size_t)r * D + e0)); __builtin_nontemporal_store(o1, (f32x4*)(outf + (size_t)r * D + e0 + 4)); }
;             if (outb) { u32x4 w; w.x = cvt_pk_bf16(o0.x, o0.y); w.y = cvt_pk_bf16(o0.z, o0.w); w.z = cvt_pk_bf16(o1.x, o1.y); w.w = cvt_pk_bf16(o1.z, o1.w); *(u32x4*)(outb + (size_t)r * D + e0) = w; }
	v_add_f32_e32 v2, v88, v2
	s_waitcnt lgkmcnt(1)
	v_add_f32_e32 v3, v89, v3
	v_lshl_add_u64 v[88:89], s[4:5], 0, v[16:17]
	s_add_u32 s4, s4, s10
	s_waitcnt lgkmcnt(0)
	v_add_f32_e32 v1, v1, v4
	ds_bpermute_b32 v4, v90, v2
	s_addc_u32 s5, s5, s11
	s_add_u32 s12, s12, s10
	s_addc_u32 s13, s13, s11
	s_cmp_lt_i32 s9, 0x10000
	s_waitcnt lgkmcnt(0)
	v_add_f32_e32 v2, v2, v4
	ds_bpermute_b32 v4, v90, v3
	s_waitcnt lgkmcnt(0)
	v_add_f32_e32 v3, v3, v4
	ds_bpermute_b32 v4, v90, v0
	s_waitcnt lgkmcnt(0)
	v_add_f32_e32 v0, v0, v4
	ds_bpermute_b32 v4, v91, v1
	s_waitcnt lgkmcnt(0)
	v_add_f32_e32 v1, v1, v4
	ds_bpermute_b32 v4, v91, v2
	s_waitcnt lgkmcnt(0)
	v_add_f32_e32 v2, v2, v4
	ds_bpermute_b32 v4, v91, v3
	s_waitcnt lgkmcnt(0)
	v_add_f32_e32 v3, v3, v4
	ds_bpermute_b32 v4, v91, v0
	s_waitcnt lgkmcnt(0)
	v_add_f32_e32 v0, v0, v4
	ds_bpermute_b32 v4, v92, v1
	s_waitcnt lgkmcnt(0)
	v_add_f32_e32 v1, v1, v4
	ds_bpermute_b32 v4, v92, v2
	s_waitcnt lgkmcnt(0)
	v_add_f32_e32 v2, v2, v4
	ds_bpermute_b32 v4, v92, v3
	s_waitcnt lgkmcnt(0)
	v_add_f32_e32 v3, v3, v4
	ds_bpermute_b32 v4, v92, v0
	s_waitcnt lgkmcnt(0)
	v_add_f32_e32 v0, v0, v4
	ds_bpermute_b32 v4, v93, v1
	s_waitcnt lgkmcnt(0)
	v_add_f32_e32 v1, v1, v4
	ds_bpermute_b32 v4, v93, v2
	s_waitcnt lgkmcnt(0)
	v_add_f32_e32 v2, v2, v4
	ds_bpermute_b32 v4, v93, v3
	s_waitcnt lgkmcnt(0)
	v_add_f32_e32 v3, v3, v4
	ds_bpermute_b32 v4, v93, v0
	s_waitcnt lgkmcnt(0)
	v_add_f32_e32 v0, v0, v4
	ds_bpermute_b32 v4, v94, v1
	s_waitcnt lgkmcnt(0)
	v_add_f32_e32 v78, v1, v4
	ds_bpermute_b32 v1, v94, v2
	v_fmamk_f32 v78, v78, 0x3a800000, v95
	v_cmp_gt_f32_e32 vcc, s7, v78
	v_mul_f32_e32 v100, 0x4f800000, v78
	s_waitcnt lgkmcnt(0)
	v_add_f32_e32 v99, v2, v1
	ds_bpermute_b32 v1, v94, v3
	v_cndmask_b32_e32 v78, v78, v100, vcc
	v_sqrt_f32_e32 v100, v78
	s_waitcnt lgkmcnt(0)
	v_add_f32_e32 v98, v3, v1
	ds_bpermute_b32 v1, v94, v0
	v_add_u32_e32 v101, -1, v100
	v_fma_f32 v102, -v101, v100, v78
	v_cmp_ge_f32_e64 s[0:1], 0, v102
	v_add_u32_e32 v102, 1, v100
	s_waitcnt lgkmcnt(0)
	v_add_f32_e32 v97, v0, v1
	v_cndmask_b32_e64 v101, v100, v101, s[0:1]
	v_fma_f32 v100, -v102, v100, v78
	v_cmp_lt_f32_e64 s[0:1], 0, v100
	s_nop 1
	v_cndmask_b32_e64 v100, v101, v102, s[0:1]
	v_mul_f32_e32 v101, 0x37800000, v100
	v_cndmask_b32_e32 v100, v100, v101, vcc
	v_cmp_class_f32_e32 vcc, v78, v96
	s_nop 1
	v_cndmask_b32_e32 v78, v100, v78, vcc
	v_div_scale_f32 v100, s[0:1], v78, v78, 1.0
	v_rcp_f32_e32 v101, v100
	s_mov_b32 s0, 0x2a400000
	v_fma_f32 v102, -v100, v101, 1.0
	v_fmac_f32_e32 v101, v102, v101
	v_div_scale_f32 v102, vcc, 1.0, v78, 1.0
	v_mul_f32_e32 v103, v102, v101
	v_fma_f32 v104, -v100, v103, v102
	v_fmac_f32_e32 v103, v104, v101
	v_fma_f32 v100, -v100, v103, v102
	v_div_fmas_f32 v100, v100, v101, v103
	v_div_fixup_f32 v78, v100, v78, 1.0
	v_pk_mul_f32 v[80:81], v[80:81], v[78:79] op_sel_hi:[1,0]
	v_pk_mul_f32 v[84:85], v[84:85], v[78:79] op_sel_hi:[1,0]
	v_pk_mul_f32 v[82:83], v[82:83], v[78:79] op_sel_hi:[1,0]
	v_pk_mul_f32 v[22:23], v[22:23], v[78:79] op_sel_hi:[1,0]
	v_pk_mul_f32 v[24:25], v[24:25], v[78:79] op_sel_hi:[1,0]
	v_pk_mul_f32 v[26:27], v[26:27], v[78:79] op_sel_hi:[1,0]
	v_pk_mul_f32 v[28:29], v[28:29], v[78:79] op_sel:[1,0] op_sel_hi:[0,0]
	v_pk_fma_f32 v[82:83], v[200:201], v[82:83], v[208:209]
	v_pk_fma_f32 v[100:101], v[206:207], v[84:85], v[214:215]
	v_pk_fma_f32 v[80:81], v[204:205], v[80:81], v[212:213]
	v_pk_mul_f32 v[84:85], v[86:87], v[78:79] op_sel_hi:[1,0]
	s_nop 0
	v_pk_fma_f32 v[102:103], v[202:203], v[84:85], v[210:211]
	v_cvt_pk_bf16_f32 v84, v80, v81
	v_add_co_u32_e32 v80, vcc, s0, v88
	s_mov_b32 s0, 0x2a401000
	s_nop 0
	v_addc_co_u32_e32 v81, vcc, 0, v89, vcc
	v_cvt_pk_bf16_f32 v85, v100, v101
	v_cvt_pk_bf16_f32 v86, v82, v83
	v_add_co_u32_e32 v82, vcc, s0, v88
	v_cvt_pk_bf16_f32 v87, v102, v103
	s_nop 1
	v_addc_co_u32_e32 v83, vcc, 0, v89, vcc
	global_store_dwordx4 v[82:83], v[84:87], off offset:-4096
	s_nop 1
	v_fmamk_f32 v84, v99, 0x3a800000, v95
	v_cmp_gt_f32_e32 vcc, s7, v84
	v_mul_f32_e32 v85, 0x4f800000, v84
	s_nop 0
	v_cndmask_b32_e32 v84, v84, v85, vcc
	v_sqrt_f32_e32 v85, v84
	s_nop 0
	v_add_u32_e32 v86, -1, v85
	v_fma_f32 v87, -v86, v85, v84
	v_cmp_ge_f32_e64 s[0:1], 0, v87
	v_add_u32_e32 v87, 1, v85
	s_nop 0
	v_cndmask_b32_e64 v86, v85, v86, s[0:1]
	v_fma_f32 v85, -v87, v85, v84
	v_cmp_lt_f32_e64 s[0:1], 0, v85
	s_nop 1
	v_cndmask_b32_e64 v85, v86, v87, s[0:1]
	v_mul_f32_e32 v86, 0x37800000, v85
	v_cndmask_b32_e32 v85, v85, v86, vcc
	v_cmp_class_f32_e32 vcc, v84, v96
	s_nop 1
	v_cndmask_b32_e32 v84, v85, v84, vcc
	v_div_scale_f32 v85, s[0:1], v84, v84, 1.0
	v_rcp_f32_e32 v86, v85
	s_nop 0
	v_fma_f32 v87, -v85, v86, 1.0
	v_fmac_f32_e32 v86, v87, v86
	v_div_scale_f32 v87, vcc, 1.0, v84, 1.0
	v_mul_f32_e32 v88, v87, v86
	v_fma_f32 v89, -v85, v88, v87
	v_fmac_f32_e32 v88, v89, v86
	v_fma_f32 v85, -v85, v88, v87
	v_div_fmas_f32 v85, v85, v86, v88
	v_div_fixup_f32 v84, v85, v84, 1.0
	v_pk_mul_f32 v[70:71], v[70:71], v[84:85] op_sel_hi:[1,0]
	v_pk_mul_f32 v[72:73], v[72:73], v[84:85] op_sel_hi:[1,0]
	v_pk_fma_f32 v[70:71], v[204:205], v[70:71], v[212:213]
	v_pk_mul_f32 v[74:75], v[74:75], v[84:85] op_sel_hi:[1,0]
	v_pk_mul_f32 v[76:77], v[76:77], v[84:85] op_sel_hi:[1,0]
	v_pk_fma_f32 v[72:73], v[200:201], v[72:73], v[208:209]
	v_cvt_pk_bf16_f32 v70, v70, v71
	v_pk_fma_f32 v[74:75], v[206:207], v[74:75], v[214:215]
	v_pk_fma_f32 v[76:77], v[202:203], v[76:77], v[210:211]
	v_cvt_pk_bf16_f32 v71, v74, v75
	v_cvt_pk_bf16_f32 v72, v72, v73
	s_nop 0
	v_cvt_pk_bf16_f32 v73, v76, v77
	global_store_dwordx4 v[80:81], v[70:73], off offset:2048
	s_nop 1
	v_fmamk_f32 v70, v98, 0x3a800000, v95
; __device__ __forceinline__ unsigned cvt_pk_bf16(float lo, float hi) { unsigned r; asm volatile("v_cvt_pk_bf16_f32 %0, %1, %2" : "=v"(r) : "v"(lo), "v"(hi)); return r; }
; __device__ __forceinline__ void ln_rows4_b(const bf16* in, float* outf, bf16* outb, const float* g, const float* b, int lane) {
;     ...
;     for (int h = 0; h < 2; ++h) {
;         const int e0 = h * 512 + 8 * lane;
;         const f32x4 g0 = *(const f32x4*)(g + e0), g1 = *(const f32x4*)(g + e0 + 4), b0 = *(const f32x4*)(b + e0), b1 = *(const f32x4*)(b + e0 + 4);
; #pragma unroll
;         for (int r = 0; r < 4; ++r) {
;             const float rstd = 1.f / sqrtf(s2[r] * (1.f / D) + LN_EPS);
;             const f32x4 o0 = (f32x4){v[r][8 * h + 0], v[r][8 * h + 1], v[r][8 * h + 2], v[r][8 * h + 3]} * rstd * g0 + b0;
;             const f32x4 o1 = (f32x4){v[r][8 * h + 4], v[r][8 * h + 5], v[r][8 * h + 6], v[r][8 * h + 7]} * rstd * g1 + b1;
;             if (outf) { __builtin_nontemporal_store(o0, (f32x4*)(outf + (size_t)r * D + e0)); __builtin_nontemporal_store(o1, (f32x4*)(outf + (size_t)r * D + e0 + 4)); }
;             if (outb) { u32x4 w; w.x = cvt_pk_bf16(o0.x, o0.y); w.y = cvt_pk_bf16(o0.z, o0.w); w.z = cvt_pk_bf16(o1.x, o1.y); w.w = cvt_pk_bf16(o1.z, o1.w); *(u32x4*)(outb + (size_t)r * D + e0) = w; }
;         }
	v_cmp_gt_f32_e32 vcc, s7, v70
	v_mul_f32_e32 v71, 0x4f800000, v70
	s_nop 0
	v_cndmask_b32_e32 v70, v70, v71, vcc
	v_sqrt_f32_e32 v71, v70
	s_nop 0
	v_add_u32_e32 v72, -1, v71
	v_fma_f32 v73, -v72, v71, v70
	v_cmp_ge_f32_e64 s[0:1], 0, v73
	v_add_u32_e32 v73, 1, v71
	s_nop 0
	v_cndmask_b32_e64 v72, v71, v72, s[0:1]
	v_fma_f32 v71, -v73, v71, v70
	v_cmp_lt_f32_e64 s[0:1], 0, v71
	s_nop 1
	v_cndmask_b32_e64 v71, v72, v73, s[0:1]
	v_mul_f32_e32 v72, 0x37800000, v71
	v_cndmask_b32_e32 v71, v71, v72, vcc
	v_cmp_class_f32_e32 vcc, v70, v96
	s_nop 1
	v_cndmask_b32_e32 v70, v71, v70, vcc
	v_div_scale_f32 v71, s[0:1], v70, v70, 1.0
	v_rcp_f32_e32 v72, v71
	s_nop 0
	v_fma_f32 v73, -v71, v72, 1.0
	v_fmac_f32_e32 v72, v73, v72
	v_div_scale_f32 v73, vcc, 1.0, v70, 1.0
	v_mul_f32_e32 v74, v73, v72
	v_fma_f32 v75, -v71, v74, v73
	v_fmac_f32_e32 v74, v75, v72
	v_fma_f32 v71, -v71, v74, v73
	v_div_fmas_f32 v71, v71, v72, v74
	v_div_fixup_f32 v70, v71, v70, 1.0
	v_pk_mul_f32 v[62:63], v[62:63], v[70:71] op_sel_hi:[1,0]
	v_pk_mul_f32 v[64:65], v[64:65], v[70:71] op_sel_hi:[1,0]
	v_pk_fma_f32 v[62:63], v[204:205], v[62:63], v[212:213]
	v_pk_mul_f32 v[66:67], v[66:67], v[70:71] op_sel_hi:[1,0]
	v_pk_mul_f32 v[68:69], v[68:69], v[70:71] op_sel_hi:[1,0]
	v_pk_fma_f32 v[64:65], v[200:201], v[64:65], v[208:209]
	v_cvt_pk_bf16_f32 v62, v62, v63
	v_pk_fma_f32 v[66:67], v[206:207], v[66:67], v[214:215]
	v_pk_fma_f32 v[68:69], v[202:203], v[68:69], v[210:211]
	v_cvt_pk_bf16_f32 v63, v66, v67
	v_cvt_pk_bf16_f32 v64, v64, v65
	s_nop 0
	v_cvt_pk_bf16_f32 v65, v68, v69
	global_store_dwordx4 v[82:83], v[62:65], off
	s_nop 1
	v_fmamk_f32 v62, v97, 0x3a800000, v95
	v_cmp_gt_f32_e32 vcc, s7, v62
	v_mul_f32_e32 v63, 0x4f800000, v62
	s_nop 0
	v_cndmask_b32_e32 v62, v62, v63, vcc
	v_sqrt_f32_e32 v63, v62
	s_nop 0
	v_add_u32_e32 v64, -1, v63
	v_fma_f32 v65, -v64, v63, v62
	v_cmp_ge_f32_e64 s[0:1], 0, v65
	v_add_u32_e32 v65, 1, v63
	s_nop 0
	v_cndmask_b32_e64 v64, v63, v64, s[0:1]
	v_fma_f32 v63, -v65, v63, v62
	v_cmp_lt_f32_e64 s[0:1], 0, v63
	s_nop 1
	v_cndmask_b32_e64 v63, v64, v65, s[0:1]
	v_mul_f32_e32 v64, 0x37800000, v63
	v_cndmask_b32_e32 v63, v63, v64, vcc
	v_cmp_class_f32_e32 vcc, v62, v96
	s_nop 1
	v_cndmask_b32_e32 v62, v63, v62, vcc
	v_div_scale_f32 v63, s[0:1], v62, v62, 1.0
	v_rcp_f32_e32 v64, v63
	s_nop 0
	v_fma_f32 v65, -v63, v64, 1.0
	v_fmac_f32_e32 v64, v65, v64
	v_div_scale_f32 v65, vcc, 1.0, v62, 1.0
	v_mul_f32_e32 v66, v65, v64
	v_fma_f32 v67, -v63, v66, v65
	v_fmac_f32_e32 v66, v67, v64
	v_fma_f32 v63, -v63, v66, v65
	v_div_fmas_f32 v63, v63, v64, v66
	v_div_fixup_f32 v62, v63, v62, 1.0
	v_pk_mul_f32 v[58:59], v[58:59], v[62:63] op_sel_hi:[1,0]
	v_pk_mul_f32 v[60:61], v[60:61], v[62:63] op_sel_hi:[1,0]
	v_pk_fma_f32 v[8:9], v[204:205], v[58:59], v[212:213]
	v_pk_fma_f32 v[10:11], v[206:207], v[60:61], v[214:215]
	v_pk_mul_f32 v[12:13], v[54:55], v[62:63] op_sel_hi:[1,0]
	v_pk_mul_f32 v[14:15], v[56:57], v[62:63] op_sel_hi:[1,0]
	s_nop 0
	v_pk_fma_f32 v[6:7], v[202:203], v[14:15], v[210:211]
	v_pk_fma_f32 v[2:3], v[200:201], v[12:13], v[208:209]
	v_cvt_pk_bf16_f32 v0, v8, v9
	v_cvt_pk_bf16_f32 v1, v10, v11
	s_nop 0
	v_cvt_pk_bf16_f32 v2, v2, v3
	v_cvt_pk_bf16_f32 v3, v6, v7
	global_store_dwordx4 v[82:83], v[0:3], off offset:2048
	s_nop 0
	v_pk_fma_f32 v[24:25], v[24:25], v[216:217], v[224:225]
	v_pk_fma_f32 v[22:23], v[22:23], v[220:221], v[228:229]
	v_pk_fma_f32 v[26:27], v[26:27], v[222:223], v[230:231]
	v_pk_fma_f32 v[28:29], v[28:29], v[218:219], v[226:227]
	v_cvt_pk_bf16_f32 v22, v22, v23
	v_cvt_pk_bf16_f32 v23, v26, v27
	v_cvt_pk_bf16_f32 v24, v24, v25
	v_pk_mul_f32 v[26:27], v[32:33], v[84:85] op_sel_hi:[1,0]
	v_cvt_pk_bf16_f32 v25, v28, v29
	global_store_dwordx4 v[80:81], v[22:25], off offset:1024
	v_pk_mul_f32 v[28:29], v[36:37], v[84:85] op_sel:[1,0] op_sel_hi:[0,0]
	v_pk_fma_f32 v[28:29], v[28:29], v[218:219], v[226:227]
	v_pk_mul_f32 v[22:23], v[30:31], v[84:85] op_sel_hi:[1,0]
	v_pk_mul_f32 v[24:25], v[34:35], v[84:85] op_sel_hi:[1,0]
	v_pk_fma_f32 v[22:23], v[22:23], v[220:221], v[228:229]
	v_pk_fma_f32 v[24:25], v[24:25], v[222:223], v[230:231]
	v_pk_fma_f32 v[26:27], v[26:27], v[216:217], v[224:225]
	v_cvt_pk_bf16_f32 v22, v22, v23
	v_cvt_pk_bf16_f32 v23, v24, v25
	s_nop 0
	v_cvt_pk_bf16_f32 v24, v26, v27
	v_cvt_pk_bf16_f32 v25, v28, v29
	global_store_dwordx4 v[80:81], v[22:25], off offset:3072
	v_pk_mul_f32 v[26:27], v[40:41], v[70:71] op_sel_hi:[1,0]
	v_pk_mul_f32 v[28:29], v[44:45], v[70:71] op_sel:[1,0] op_sel_hi:[0,0]
	v_pk_mul_f32 v[22:23], v[38:39], v[70:71] op_sel_hi:[1,0]
	v_pk_mul_f32 v[24:25], v[42:43], v[70:71] op_sel_hi:[1,0]
	v_pk_fma_f32 v[22:23], v[22:23], v[220:221], v[228:229]
	v_pk_fma_f32 v[24:25], v[24:25], v[222:223], v[230:231]
	v_pk_fma_f32 v[28:29], v[28:29], v[218:219], v[226:227]
	v_pk_fma_f32 v[26:27], v[26:27], v[216:217], v[224:225]
	v_cvt_pk_bf16_f32 v22, v22, v23
	v_cvt_pk_bf16_f32 v23, v24, v25
	s_nop 0
	v_cvt_pk_bf16_f32 v24, v26, v27
	v_cvt_pk_bf16_f32 v25, v28, v29
	global_store_dwordx4 v[82:83], v[22:25], off offset:1024
	s_nop 1
	v_pk_mul_f32 v[22:23], v[46:47], v[62:63] op_sel_hi:[1,0]
	v_pk_mul_f32 v[24:25], v[50:51], v[62:63] op_sel_hi:[1,0]
	v_pk_fma_f32 v[4:5], v[22:23], v[220:221], v[228:229]
	v_pk_fma_f32 v[6:7], v[24:25], v[222:223], v[230:231]
	v_pk_mul_f32 v[12:13], v[48:49], v[62:63] op_sel_hi:[1,0]
	v_pk_mul_f32 v[14:15], v[52:53], v[62:63] op_sel:[1,0] op_sel_hi:[0,0]
	v_pk_fma_f32 v[10:11], v[14:15], v[218:219], v[226:227]
	v_pk_fma_f32 v[2:3], v[12:13], v[216:217], v[224:225]
	v_cvt_pk_bf16_f32 v0, v4, v5
	v_cvt_pk_bf16_f32 v1, v6, v7
	s_nop 0
	v_cvt_pk_bf16_f32 v2, v2, v3
	v_cvt_pk_bf16_f32 v3, v10, v11
	global_store_dwordx4 v[82:83], v[0:3], off offset:3072
	s_cbranch_scc1 .LBB0_814
